# speedup vs baseline: 1.0056x; 1.0030x over previous
; #define SBAR() __builtin_amdgcn_sched_barrier(0)
; #define HBAR(n) do { asm volatile("s_waitcnt vmcnt(" #n ") lgkmcnt(0)" ::: "memory"); __builtin_amdgcn_s_barrier(); asm volatile("" ::: "memory"); } while (0)
; #define RD2(S, k, D0) do { S##l##k = tr_read<v_rd_off(D0, k, 0)>(vb); S##h##k = tr_read<v_rd_off(D0, k, 1)>(vb); } while (0)
; #define PVB(X, Y, D0, D1) do { LW(6); MF(X, 0, D0, pa0); SBAR(); RD2(Y, 0, D1); LW(6); MF(X, 1, D0, pa1); SBAR(); RD2(Y, 1, D1); \
;     LW(6); MF(X, 2, D0, pa2); SBAR(); RD2(Y, 2, D1); LW(6); MF(X, 3, D0, pa3); SBAR(); RD2(Y, 3, D1); } while (0)
; __device__ __forceinline__ void finishSM(f32x16& p0, f32x16& p1, float alpha, float& l_reg, bf16x8& pa0, bf16x8& pa1, bf16x8& pa2, bf16x8& pa3) {
;     ...
;     PK4(p0, 0, pa0); PK4(p0, 8, pa1); PK4(p1, 0, pa2); PK4(p1, 8, pa3);
; __device__ __forceinline__ void attn_dense_body(const bf16_t* __restrict__ Qb, const bf16_t* __restrict__ Kh, const bf16_t* __restrict__ Vh,
;                                                 float* __restrict__ Ob, int seq, char* lds, LAS unsigned char* lds3, const int tid) {
;     ...
;         const int vb = vb0 + b * (int)SHM_V;
;         s16x4 Al0, Ah0, Al1, Ah1, Al2, Ah2, Al3, Ah3, Bl0, Bh0, Bl1, Bh1, Bl2, Bh2, Bl3, Bh3;
;     ...
;         HBAR(6);
;         SBAR();
;         {
;     ...
;           __builtin_amdgcn_s_setprio(1);
;           RD2(A, 0, 0); RD2(A, 1, 0); RD2(A, 2, 0); RD2(A, 3, 0);
;           PVB(A, B, 0, 1); PVB(B, A, 1, 2); PVB(A, B, 2, 3); PVB(B, A, 3, 4); PVB(A, B, 4, 5); PVB(B, A, 5, 6); PVB(A, B, 6, 7);
.Lat_cont:
	v_add_f32_e32 v245, v245, v0
	v_add_f32_e32 v229, v229, v14
	v_cvt_pk_bf16_f32 v2, v160, v161
	v_cvt_pk_bf16_f32 v3, v162, v163
	v_cvt_pk_bf16_f32 v4, v168, v169
	v_cvt_pk_bf16_f32 v5, v170, v171
	v_cvt_pk_bf16_f32 v6, v176, v177
	v_cvt_pk_bf16_f32 v7, v178, v179
	v_cvt_pk_bf16_f32 v8, v184, v185
	v_cvt_pk_bf16_f32 v9, v186, v187
	v_cvt_pk_bf16_f32 v10, v164, v165
	v_cvt_pk_bf16_f32 v11, v166, v167
	v_cvt_pk_bf16_f32 v12, v172, v173
	v_cvt_pk_bf16_f32 v13, v174, v175
	v_cvt_pk_bf16_f32 v152, v180, v181
	v_cvt_pk_bf16_f32 v153, v182, v183
	v_cvt_pk_bf16_f32 v154, v188, v189
	v_cvt_pk_bf16_f32 v155, v190, v191
	v_lshl_add_u32 v14, s91, 15, v247
	ds_read_b64_tr_b16 v[160:161], v14 offset:0
	ds_read_b64_tr_b16 v[162:163], v14 offset:8192
	ds_read_b64_tr_b16 v[164:165], v14 offset:256
	ds_read_b64_tr_b16 v[166:167], v14 offset:8448
	ds_read_b64_tr_b16 v[168:169], v14 offset:512
	ds_read_b64_tr_b16 v[170:171], v14 offset:8704
	ds_read_b64_tr_b16 v[172:173], v14 offset:768
	ds_read_b64_tr_b16 v[174:175], v14 offset:8960
	ds_read_b64_tr_b16 v[176:177], v14 offset:1024
	ds_read_b64_tr_b16 v[178:179], v14 offset:9216
	ds_read_b64_tr_b16 v[180:181], v14 offset:1280
	ds_read_b64_tr_b16 v[182:183], v14 offset:9472
	ds_read_b64_tr_b16 v[184:185], v14 offset:1536
	ds_read_b64_tr_b16 v[186:187], v14 offset:9728
	ds_read_b64_tr_b16 v[188:189], v14 offset:1792
	ds_read_b64_tr_b16 v[190:191], v14 offset:9984
	v_lshl_add_u32 v232, s99, 14, v246
	v_add_u32_e32 v0, v239, v232
	v_xad_u32 v15, v239, 64, v232
	v_xad_u32 v231, v239, s60, v232
	s_movk_i32 s0, 0xc0
	v_xad_u32 v232, v239, s0, v232
	s_waitcnt vmcnt(6) lgkmcnt(0)
	s_barrier
	s_setprio 1
	v_mfma_f32_16x16x32_bf16 v[16:19], v[2:5], v[160:163], v[16:19]
	v_mfma_f32_16x16x32_bf16 v[80:83], v[10:13], v[160:163], v[80:83]
	v_mfma_f32_16x16x32_bf16 v[20:23], v[2:5], v[164:167], v[20:23]
	ds_read_b64_tr_b16 v[160:161], v14 offset:16384
	v_mfma_f32_16x16x32_bf16 v[84:87], v[10:13], v[164:167], v[84:87]
	ds_read_b64_tr_b16 v[162:163], v14 offset:24576
	v_mfma_f32_16x16x32_bf16 v[24:27], v[2:5], v[168:171], v[24:27]
	ds_read_b64_tr_b16 v[164:165], v14 offset:16640
	v_mfma_f32_16x16x32_bf16 v[88:91], v[10:13], v[168:171], v[88:91]
	ds_read_b64_tr_b16 v[166:167], v14 offset:24832
	v_mfma_f32_16x16x32_bf16 v[28:31], v[2:5], v[172:175], v[28:31]
	ds_read_b64_tr_b16 v[168:169], v14 offset:16896
	v_mfma_f32_16x16x32_bf16 v[92:95], v[10:13], v[172:175], v[92:95]
	ds_read_b64_tr_b16 v[170:171], v14 offset:25088
	v_mfma_f32_16x16x32_bf16 v[32:35], v[2:5], v[176:179], v[32:35]
	ds_read_b64_tr_b16 v[172:173], v14 offset:17152
	v_mfma_f32_16x16x32_bf16 v[96:99], v[10:13], v[176:179], v[96:99]
	ds_read_b64_tr_b16 v[174:175], v14 offset:25344
	v_mfma_f32_16x16x32_bf16 v[36:39], v[2:5], v[180:183], v[36:39]
	ds_read_b64_tr_b16 v[176:177], v14 offset:17408
	v_mfma_f32_16x16x32_bf16 v[100:103], v[10:13], v[180:183], v[100:103]
	ds_read_b64_tr_b16 v[178:179], v14 offset:25600
	v_mfma_f32_16x16x32_bf16 v[40:43], v[2:5], v[184:187], v[40:43]
	ds_read_b64_tr_b16 v[180:181], v14 offset:17664
	v_mfma_f32_16x16x32_bf16 v[104:107], v[10:13], v[184:187], v[104:107]
	ds_read_b64_tr_b16 v[182:183], v14 offset:25856
	v_mfma_f32_16x16x32_bf16 v[44:47], v[2:5], v[188:191], v[44:47]
	ds_read_b64_tr_b16 v[184:185], v14 offset:17920
	v_mfma_f32_16x16x32_bf16 v[108:111], v[10:13], v[188:191], v[108:111]
	ds_read_b64_tr_b16 v[186:187], v14 offset:26112
	s_waitcnt lgkmcnt(10)
	v_mfma_f32_16x16x32_bf16 v[16:19], v[6:9], v[160:163], v[16:19]
	ds_read_b64_tr_b16 v[188:189], v14 offset:18176
	v_mfma_f32_16x16x32_bf16 v[80:83], v[152:155], v[160:163], v[80:83]
	ds_read_b64_tr_b16 v[190:191], v14 offset:26368
	v_mfma_f32_16x16x32_bf16 v[20:23], v[6:9], v[164:167], v[20:23]
	ds_read_b64_tr_b16 v[160:161], v14 offset:2048
	v_mfma_f32_16x16x32_bf16 v[84:87], v[152:155], v[164:167], v[84:87]
	ds_read_b64_tr_b16 v[162:163], v14 offset:10240
	s_waitcnt lgkmcnt(10)
	v_mfma_f32_16x16x32_bf16 v[24:27], v[6:9], v[168:171], v[24:27]
	ds_read_b64_tr_b16 v[164:165], v14 offset:18432
	v_mfma_f32_16x16x32_bf16 v[88:91], v[152:155], v[168:171], v[88:91]
	ds_read_b64_tr_b16 v[166:167], v14 offset:26624
	v_mfma_f32_16x16x32_bf16 v[28:31], v[6:9], v[172:175], v[28:31]
	ds_read_b64_tr_b16 v[168:169], v14 offset:2304
	v_mfma_f32_16x16x32_bf16 v[92:95], v[152:155], v[172:175], v[92:95]
	ds_read_b64_tr_b16 v[170:171], v14 offset:10496
	s_waitcnt lgkmcnt(10)
	v_mfma_f32_16x16x32_bf16 v[32:35], v[6:9], v[176:179], v[32:35]
	ds_read_b64_tr_b16 v[172:173], v14 offset:18688
	v_mfma_f32_16x16x32_bf16 v[96:99], v[152:155], v[176:179], v[96:99]
	ds_read_b64_tr_b16 v[174:175], v14 offset:26880
	v_mfma_f32_16x16x32_bf16 v[36:39], v[6:9], v[180:183], v[36:39]
	ds_read_b64_tr_b16 v[176:177], v14 offset:2560
	v_mfma_f32_16x16x32_bf16 v[100:103], v[152:155], v[180:183], v[100:103]
	ds_read_b64_tr_b16 v[178:179], v14 offset:10752
	s_waitcnt lgkmcnt(10)
	v_mfma_f32_16x16x32_bf16 v[40:43], v[6:9], v[184:187], v[40:43]
	ds_read_b64_tr_b16 v[180:181], v14 offset:18944
	v_mfma_f32_16x16x32_bf16 v[104:107], v[152:155], v[184:187], v[104:107]
	ds_read_b64_tr_b16 v[182:183], v14 offset:27136
	v_mfma_f32_16x16x32_bf16 v[44:47], v[6:9], v[188:191], v[44:47]
	ds_read_b64_tr_b16 v[184:185], v14 offset:2816
	v_mfma_f32_16x16x32_bf16 v[108:111], v[152:155], v[188:191], v[108:111]
	ds_read_b64_tr_b16 v[186:187], v14 offset:11008
	s_waitcnt lgkmcnt(10)
; #define SBAR() __builtin_amdgcn_sched_barrier(0)
; #define KM(d0, B0, B1) do { p0 = __builtin_amdgcn_mfma_f32_32x32x16_bf16(B0, qr[d0], p0, 0, 0, 0); p1 = __builtin_amdgcn_mfma_f32_32x32x16_bf16(B1, qr[d0], p1, 0, 0, 0); } while (0)
; #define HBAR(n) do { asm volatile("s_waitcnt vmcnt(" #n ") lgkmcnt(0)" ::: "memory"); __builtin_amdgcn_s_barrier(); asm volatile("" ::: "memory"); } while (0)
; #define LW(n) do { asm volatile("s_waitcnt lgkmcnt(" #n ")" ::: "memory"); SBAR(); } while (0)
; #define RD2(S, k, D0) do { S##l##k = tr_read<v_rd_off(D0, k, 0)>(vb); S##h##k = tr_read<v_rd_off(D0, k, 1)>(vb); } while (0)
; #define LW(n) do { asm volatile("s_waitcnt lgkmcnt(" #n ")" ::: "memory"); SBAR(); } while (0)
; __device__ __forceinline__ void attn_dense_body(const bf16_t* __restrict__ Qb, const bf16_t* __restrict__ Kh, const bf16_t* __restrict__ Vh,
;                                                 float* __restrict__ Ob, int seq, char* lds, LAS unsigned char* lds3, const int tid) {
;     ...
;           __builtin_amdgcn_s_setprio(1);
;           RD2(A, 0, 0); RD2(A, 1, 0); RD2(A, 2, 0); RD2(A, 3, 0);
;           PVB(A, B, 0, 1); PVB(B, A, 1, 2); PVB(A, B, 2, 3); PVB(B, A, 3, 4); PVB(A, B, 4, 5); PVB(B, A, 5, 6); PVB(A, B, 6, 7);
;           const int kadr = (int)(uintptr_t)K_lds + b1 * (int)SHM_K + r32 * 256; int kt = (hi * 16) ^ ((r32 & 7) << 4);
;           asm volatile("" : "+v"(kt));
;           bf16x8 k0a, k0b, k1a, k1b, k2a, k2b;
;     ...
;           LW(6); MF(B, 0, 7, pa0); SBAR(); KRD(0, k0a, k0b);
;           LW(6); MF(B, 1, 7, pa1); SBAR(); KRD(1, k1a, k1b);
;           LW(6); MF(B, 2, 7, pa2); SBAR(); KRD(2, k2a, k2b);
;           LW(6); MF(B, 3, 7, pa3); SBAR();
;           LW(4); p0 = __builtin_amdgcn_mfma_f32_32x32x16_bf16(k0a, qr[0], nm, 0, 0, 0); p1 = __builtin_amdgcn_mfma_f32_32x32x16_bf16(k0b, qr[0], nm, 0, 0, 0); SBAR(); KRD(3, k0a, k0b);
;           LW(4); KM(1, k1a, k1b); SBAR(); KRD(4, k1a, k1b);
;           LW(4); KM(2, k2a, k2b); SBAR(); KRD(5, k2a, k2b);
;           LW(4); KM(3, k0a, k0b); SBAR(); KRD(6, k0a, k0b);
;           LW(4); KM(4, k1a, k1b); SBAR(); KRD(7, k1a, k1b);
;           LW(4); KM(5, k2a, k2b); SBAR();
;           LW(2); KM(6, k0a, k0b); SBAR();
;           LW(0); KM(7, k1a, k1b);
;           __builtin_amdgcn_s_setprio(0);
;     ...
;         }
;     ...
;         HBAR(0);
;         { const int t_ = b; b = b1; b1 = b2; b2 = t_; }
	v_mfma_f32_16x16x32_bf16 v[48:51], v[2:5], v[160:163], v[48:51]
	ds_read_b64_tr_b16 v[188:189], v14 offset:19200
	v_mfma_f32_16x16x32_bf16 v[112:115], v[10:13], v[160:163], v[112:115]
	ds_read_b64_tr_b16 v[190:191], v14 offset:27392
	v_mfma_f32_16x16x32_bf16 v[48:51], v[6:9], v[164:167], v[48:51]
	ds_read_b64_tr_b16 v[160:161], v14 offset:3072
	v_mfma_f32_16x16x32_bf16 v[112:115], v[152:155], v[164:167], v[112:115]
	ds_read_b64_tr_b16 v[162:163], v14 offset:11264
	s_waitcnt lgkmcnt(10)
	v_mfma_f32_16x16x32_bf16 v[52:55], v[2:5], v[168:171], v[52:55]
	ds_read_b64_tr_b16 v[164:165], v14 offset:19456
	v_mfma_f32_16x16x32_bf16 v[116:119], v[10:13], v[168:171], v[116:119]
	ds_read_b64_tr_b16 v[166:167], v14 offset:27648
	v_mfma_f32_16x16x32_bf16 v[52:55], v[6:9], v[172:175], v[52:55]
	ds_read_b64_tr_b16 v[168:169], v14 offset:3328
	v_mfma_f32_16x16x32_bf16 v[116:119], v[152:155], v[172:175], v[116:119]
	ds_read_b64_tr_b16 v[170:171], v14 offset:11520
	s_waitcnt lgkmcnt(10)
	v_mfma_f32_16x16x32_bf16 v[56:59], v[2:5], v[176:179], v[56:59]
	ds_read_b64_tr_b16 v[172:173], v14 offset:19712
	v_mfma_f32_16x16x32_bf16 v[120:123], v[10:13], v[176:179], v[120:123]
	ds_read_b64_tr_b16 v[174:175], v14 offset:27904
	v_mfma_f32_16x16x32_bf16 v[56:59], v[6:9], v[180:183], v[56:59]
	ds_read_b64_tr_b16 v[176:177], v14 offset:3584
	v_mfma_f32_16x16x32_bf16 v[120:123], v[152:155], v[180:183], v[120:123]
	ds_read_b64_tr_b16 v[178:179], v14 offset:11776
	s_waitcnt lgkmcnt(10)
	v_mfma_f32_16x16x32_bf16 v[60:63], v[2:5], v[184:187], v[60:63]
	ds_read_b64_tr_b16 v[180:181], v14 offset:19968
	v_mfma_f32_16x16x32_bf16 v[124:127], v[10:13], v[184:187], v[124:127]
	ds_read_b64_tr_b16 v[182:183], v14 offset:28160
	v_mfma_f32_16x16x32_bf16 v[60:63], v[6:9], v[188:191], v[60:63]
	ds_read_b64_tr_b16 v[184:185], v14 offset:3840
	v_mfma_f32_16x16x32_bf16 v[124:127], v[152:155], v[188:191], v[124:127]
	ds_read_b64_tr_b16 v[186:187], v14 offset:12032
	s_waitcnt lgkmcnt(10)
	v_mfma_f32_16x16x32_bf16 v[64:67], v[2:5], v[160:163], v[64:67]
	ds_read_b64_tr_b16 v[188:189], v14 offset:20224
	v_mfma_f32_16x16x32_bf16 v[128:131], v[10:13], v[160:163], v[128:131]
	ds_read_b64_tr_b16 v[190:191], v14 offset:28416
	v_mfma_f32_16x16x32_bf16 v[64:67], v[6:9], v[164:167], v[64:67]
	v_mfma_f32_16x16x32_bf16 v[128:131], v[152:155], v[164:167], v[128:131]
	s_waitcnt lgkmcnt(8)
	v_mfma_f32_16x16x32_bf16 v[68:71], v[2:5], v[168:171], v[68:71]
	v_mfma_f32_16x16x32_bf16 v[132:135], v[10:13], v[168:171], v[132:135]
	v_mfma_f32_16x16x32_bf16 v[68:71], v[6:9], v[172:175], v[68:71]
	v_mfma_f32_16x16x32_bf16 v[132:135], v[152:155], v[172:175], v[132:135]
	s_waitcnt lgkmcnt(4)
	v_mfma_f32_16x16x32_bf16 v[72:75], v[2:5], v[176:179], v[72:75]
	v_mfma_f32_16x16x32_bf16 v[136:139], v[10:13], v[176:179], v[136:139]
	ds_read_b128 v[156:159], v0 offset:0
	v_mfma_f32_16x16x32_bf16 v[72:75], v[6:9], v[180:183], v[72:75]
	v_mfma_f32_16x16x32_bf16 v[136:139], v[152:155], v[180:183], v[136:139]
	ds_read_b128 v[224:227], v15 offset:0
	s_waitcnt lgkmcnt(2)
	v_mfma_f32_16x16x32_bf16 v[76:79], v[2:5], v[184:187], v[76:79]
	v_mfma_f32_16x16x32_bf16 v[140:143], v[10:13], v[184:187], v[140:143]
	ds_read_b128 v[234:237], v231 offset:0
	v_mfma_f32_16x16x32_bf16 v[76:79], v[6:9], v[188:191], v[76:79]
	v_mfma_f32_16x16x32_bf16 v[140:143], v[152:155], v[188:191], v[140:143]
	ds_read_b128 v[248:251], v232 offset:0
	ds_read_b128 v[2:5], v0 offset:4096
	ds_read_b128 v[6:9], v15 offset:4096
	ds_read_b128 v[10:13], v231 offset:4096
	ds_read_b128 v[152:155], v232 offset:4096
	s_waitcnt lgkmcnt(7)
	v_mfma_f32_16x16x32_bf16 v[160:163], v[156:159], v[192:195], v[144:147]
	v_mfma_f32_16x16x32_bf16 v[164:167], v[156:159], v[208:211], v[148:151]
	ds_read_b128 v[156:159], v0 offset:8192
	s_waitcnt lgkmcnt(7)
	v_mfma_f32_16x16x32_bf16 v[160:163], v[224:227], v[196:199], v[160:163]
	v_mfma_f32_16x16x32_bf16 v[164:167], v[224:227], v[212:215], v[164:167]
	ds_read_b128 v[224:227], v15 offset:8192
	s_waitcnt lgkmcnt(7)
	v_mfma_f32_16x16x32_bf16 v[160:163], v[234:237], v[200:203], v[160:163]
	v_mfma_f32_16x16x32_bf16 v[164:167], v[234:237], v[216:219], v[164:167]
	ds_read_b128 v[234:237], v231 offset:8192
	s_waitcnt lgkmcnt(7)
	v_mfma_f32_16x16x32_bf16 v[160:163], v[248:251], v[204:207], v[160:163]
	v_mfma_f32_16x16x32_bf16 v[164:167], v[248:251], v[220:223], v[164:167]
	ds_read_b128 v[248:251], v232 offset:8192
	s_waitcnt lgkmcnt(7)
	v_mfma_f32_16x16x32_bf16 v[168:171], v[2:5], v[192:195], v[144:147]
	v_mfma_f32_16x16x32_bf16 v[172:175], v[2:5], v[208:211], v[148:151]
	ds_read_b128 v[2:5], v0 offset:12288
	s_waitcnt lgkmcnt(7)
	v_mfma_f32_16x16x32_bf16 v[168:171], v[6:9], v[196:199], v[168:171]
	v_mfma_f32_16x16x32_bf16 v[172:175], v[6:9], v[212:215], v[172:175]
	ds_read_b128 v[6:9], v15 offset:12288
	s_waitcnt lgkmcnt(7)
	v_mfma_f32_16x16x32_bf16 v[168:171], v[10:13], v[200:203], v[168:171]
	v_mfma_f32_16x16x32_bf16 v[172:175], v[10:13], v[216:219], v[172:175]
	ds_read_b128 v[10:13], v231 offset:12288
	s_waitcnt lgkmcnt(7)
	v_mfma_f32_16x16x32_bf16 v[168:171], v[152:155], v[204:207], v[168:171]
	v_mfma_f32_16x16x32_bf16 v[172:175], v[152:155], v[220:223], v[172:175]
	ds_read_b128 v[152:155], v232 offset:12288
	s_waitcnt lgkmcnt(7)
	v_mfma_f32_16x16x32_bf16 v[176:179], v[156:159], v[192:195], v[144:147]
	v_mfma_f32_16x16x32_bf16 v[180:183], v[156:159], v[208:211], v[148:151]
	s_waitcnt lgkmcnt(6)
	v_mfma_f32_16x16x32_bf16 v[176:179], v[224:227], v[196:199], v[176:179]
	v_mfma_f32_16x16x32_bf16 v[180:183], v[224:227], v[212:215], v[180:183]
	s_waitcnt lgkmcnt(5)
	v_mfma_f32_16x16x32_bf16 v[176:179], v[234:237], v[200:203], v[176:179]
	v_mfma_f32_16x16x32_bf16 v[180:183], v[234:237], v[216:219], v[180:183]
	s_waitcnt lgkmcnt(4)
	v_mfma_f32_16x16x32_bf16 v[176:179], v[248:251], v[204:207], v[176:179]
	v_mfma_f32_16x16x32_bf16 v[180:183], v[248:251], v[220:223], v[180:183]
	s_waitcnt lgkmcnt(3)
	v_mfma_f32_16x16x32_bf16 v[184:187], v[2:5], v[192:195], v[144:147]
	v_mfma_f32_16x16x32_bf16 v[188:191], v[2:5], v[208:211], v[148:151]
	s_waitcnt lgkmcnt(2)
	v_mfma_f32_16x16x32_bf16 v[184:187], v[6:9], v[196:199], v[184:187]
	v_mfma_f32_16x16x32_bf16 v[188:191], v[6:9], v[212:215], v[188:191]
	s_waitcnt lgkmcnt(1)
	v_mfma_f32_16x16x32_bf16 v[184:187], v[10:13], v[200:203], v[184:187]
	v_mfma_f32_16x16x32_bf16 v[188:191], v[10:13], v[216:219], v[188:191]
	s_waitcnt lgkmcnt(0)
	v_mfma_f32_16x16x32_bf16 v[184:187], v[152:155], v[204:207], v[184:187]
	v_mfma_f32_16x16x32_bf16 v[188:191], v[152:155], v[220:223], v[188:191]
	s_setprio 0
	s_waitcnt vmcnt(0) lgkmcnt(0)
	s_barrier
	s_cmp_eq_u32 s15, s89
	s_cbranch_scc1 .Lat_done
	s_mov_b32 s0, s99
	s_mov_b32 s99, s10
	s_mov_b32 s10, s91
	s_branch .Lat_loop
